# attention softmax row max as four independent max3 chains instead of one 17-deep dependent chain (on top of the bias-vector variant)
# speedup vs baseline: 1.0125x; 1.0055x over previous
.Latt3_A_loop:
	v_add_u32_e32 v209, s70, v215
	v_add_u32_e32 v205, s70, v216
	ds_read_b128 v[226:229], v209
	ds_read_b128 v[236:239], v209 offset:12800
	ds_read_b128 v[240:243], v209 offset:32
	ds_read_b128 v[244:247], v209 offset:12832
	ds_read_b128 v[248:251], v209 offset:64
	ds_read_b128 v[210:213], v209 offset:12864
	s_waitcnt lgkmcnt(5)
	v_mfma_f32_32x32x16_bf16 v[82:97], v[226:229], v[126:129], v[188:203]
	ds_read_b128 v[226:229], v209 offset:96
	s_waitcnt lgkmcnt(5)
	v_mfma_f32_32x32x16_bf16 v[66:81], v[236:239], v[126:129], v[188:203]
	ds_read_b128 v[236:239], v209 offset:12896
	s_waitcnt lgkmcnt(5)
	v_mfma_f32_32x32x16_bf16 v[82:97], v[240:243], v[142:145], v[82:97]
	ds_read_b128 v[240:243], v209 offset:128
	s_waitcnt lgkmcnt(5)
	v_mfma_f32_32x32x16_bf16 v[66:81], v[244:247], v[142:145], v[66:81]
	ds_read_b128 v[244:247], v209 offset:12928
	s_waitcnt lgkmcnt(5)
	v_mfma_f32_32x32x16_bf16 v[82:97], v[248:251], v[146:149], v[82:97]
	ds_read_b128 v[248:251], v209 offset:160
	s_waitcnt lgkmcnt(5)
	v_mfma_f32_32x32x16_bf16 v[66:81], v[210:213], v[146:149], v[66:81]
	ds_read_b128 v[210:213], v209 offset:12960
	s_waitcnt lgkmcnt(5)
	v_mfma_f32_32x32x16_bf16 v[82:97], v[226:229], v[150:153], v[82:97]
	ds_read_b128 v[226:229], v209 offset:192
	s_waitcnt lgkmcnt(5)
	v_mfma_f32_32x32x16_bf16 v[66:81], v[236:239], v[150:153], v[66:81]
	ds_read_b128 v[236:239], v209 offset:12992
	s_waitcnt lgkmcnt(5)
	v_mfma_f32_32x32x16_bf16 v[82:97], v[240:243], v[154:157], v[82:97]
	ds_read_b128 v[240:243], v209 offset:224
	s_waitcnt lgkmcnt(5)
	v_mfma_f32_32x32x16_bf16 v[66:81], v[244:247], v[154:157], v[66:81]
	ds_read_b128 v[244:247], v209 offset:13024
	s_waitcnt lgkmcnt(5)
	v_mfma_f32_32x32x16_bf16 v[82:97], v[248:251], v[158:161], v[82:97]
	ds_read_b128 v[248:251], v209 offset:256
	s_waitcnt lgkmcnt(5)
	v_mfma_f32_32x32x16_bf16 v[66:81], v[210:213], v[158:161], v[66:81]
	ds_read_b128 v[210:213], v209 offset:13056
	s_waitcnt lgkmcnt(5)
	v_mfma_f32_32x32x16_bf16 v[82:97], v[226:229], v[162:165], v[82:97]
	ds_read_b128 v[226:229], v209 offset:288
	s_waitcnt lgkmcnt(5)
	v_mfma_f32_32x32x16_bf16 v[66:81], v[236:239], v[162:165], v[66:81]
	ds_read_b128 v[236:239], v209 offset:13088
	s_waitcnt lgkmcnt(5)
	v_mfma_f32_32x32x16_bf16 v[82:97], v[240:243], v[166:169], v[82:97]
	ds_read_b128 v[240:243], v209 offset:320
	s_waitcnt lgkmcnt(5)
	v_mfma_f32_32x32x16_bf16 v[66:81], v[244:247], v[166:169], v[66:81]
	ds_read_b128 v[244:247], v209 offset:13120
	s_waitcnt lgkmcnt(5)
	v_mfma_f32_32x32x16_bf16 v[82:97], v[248:251], v[170:173], v[82:97]
	ds_read_b128 v[248:251], v209 offset:352
	s_waitcnt lgkmcnt(5)
	v_mfma_f32_32x32x16_bf16 v[66:81], v[210:213], v[170:173], v[66:81]
	ds_read_b128 v[210:213], v209 offset:13152
	s_waitcnt lgkmcnt(5)
	v_mfma_f32_32x32x16_bf16 v[82:97], v[226:229], v[174:177], v[82:97]
	s_waitcnt lgkmcnt(4)
	v_mfma_f32_32x32x16_bf16 v[66:81], v[236:239], v[174:177], v[66:81]
	s_waitcnt lgkmcnt(3)
	v_mfma_f32_32x32x16_bf16 v[82:97], v[240:243], v[178:181], v[82:97]
	s_waitcnt lgkmcnt(2)
	v_mfma_f32_32x32x16_bf16 v[66:81], v[244:247], v[178:181], v[66:81]
	s_waitcnt lgkmcnt(1)
	v_mfma_f32_32x32x16_bf16 v[82:97], v[248:251], v[182:185], v[82:97]
	s_waitcnt lgkmcnt(0)
	v_mfma_f32_32x32x16_bf16 v[66:81], v[210:213], v[182:185], v[66:81]
	s_setprio 2
	ds_read_b128 v[236:239], v205 offset:25600
	ds_read_b128 v[240:243], v205 offset:30208
	ds_read_b128 v[244:247], v205 offset:34816
	ds_read_b128 v[248:251], v205 offset:39424
	ds_read_b128 v[210:213], v205 offset:25632
	s_nop 4
	v_max3_f32 v226, v82, v83, v84
	v_max3_f32 v227, v85, v86, v87
	v_max3_f32 v228, v88, v89, v90
	v_max3_f32 v229, v91, v92, v93
	v_max3_f32 v226, v226, v94, v95
	v_max3_f32 v227, v227, v96, v97
	v_max3_f32 v228, v228, v66, v67
	v_max3_f32 v229, v229, v68, v69
	v_max3_f32 v226, v226, v70, v71
	v_max3_f32 v227, v227, v72, v73
	v_max3_f32 v228, v228, v74, v75
	v_max3_f32 v229, v229, v76, v77
	v_max3_f32 v226, v226, v78, v79
	v_max3_f32 v227, v227, v80, v81
	v_max3_f32 v186, v226, v227, v228
	v_max_f32_e32 v186, v186, v229
	v_mov_b32_e32 v187, v186
	s_nop 1
	v_permlane32_swap_b32_e32 v186, v187
	v_max_f32_e32 v187, v186, v187
	v_sub_f32_e32 v187, v187, v188
	v_add_f32_e32 v186, 0x41380000, v223
	v_cmp_gt_f32_e32 vcc, v187, v186
	s_cbranch_vccz .Latt3_nr_5
	v_max_f32_e32 v186, v187, v187
	v_max_f32_e32 v187, v223, v223
	v_max_f32_e32 v187, v187, v186
	v_sub_f32_e32 v186, v223, v187
	v_exp_f32_e32 v186, v186
	v_mov_b32_e32 v223, v187
	v_pk_mul_f32 v[64:65], v[64:65], v[186:187] op_sel_hi:[1,0]
	v_pk_mul_f32 v[62:63], v[62:63], v[186:187] op_sel_hi:[1,0]
	v_pk_mul_f32 v[60:61], v[60:61], v[186:187] op_sel_hi:[1,0]
	v_pk_mul_f32 v[58:59], v[58:59], v[186:187] op_sel_hi:[1,0]
	v_pk_mul_f32 v[56:57], v[56:57], v[186:187] op_sel_hi:[1,0]
	v_pk_mul_f32 v[54:55], v[54:55], v[186:187] op_sel_hi:[1,0]
	v_pk_mul_f32 v[52:53], v[52:53], v[186:187] op_sel_hi:[1,0]
	v_pk_mul_f32 v[50:51], v[50:51], v[186:187] op_sel_hi:[1,0]
	v_pk_mul_f32 v[48:49], v[48:49], v[186:187] op_sel_hi:[1,0]
	v_pk_mul_f32 v[46:47], v[46:47], v[186:187] op_sel_hi:[1,0]
	v_pk_mul_f32 v[44:45], v[44:45], v[186:187] op_sel_hi:[1,0]
	v_pk_mul_f32 v[42:43], v[42:43], v[186:187] op_sel_hi:[1,0]
	v_pk_mul_f32 v[40:41], v[40:41], v[186:187] op_sel_hi:[1,0]
	v_pk_mul_f32 v[38:39], v[38:39], v[186:187] op_sel_hi:[1,0]
	v_pk_mul_f32 v[36:37], v[36:37], v[186:187] op_sel_hi:[1,0]
	v_pk_mul_f32 v[34:35], v[34:35], v[186:187] op_sel_hi:[1,0]
	v_pk_mul_f32 v[32:33], v[32:33], v[186:187] op_sel_hi:[1,0]
	v_pk_mul_f32 v[30:31], v[30:31], v[186:187] op_sel_hi:[1,0]
	v_pk_mul_f32 v[28:29], v[28:29], v[186:187] op_sel_hi:[1,0]
	v_pk_mul_f32 v[26:27], v[26:27], v[186:187] op_sel_hi:[1,0]
	v_pk_mul_f32 v[24:25], v[24:25], v[186:187] op_sel_hi:[1,0]
	v_pk_mul_f32 v[22:23], v[22:23], v[186:187] op_sel_hi:[1,0]
	v_pk_mul_f32 v[20:21], v[20:21], v[186:187] op_sel_hi:[1,0]
	v_pk_mul_f32 v[18:19], v[18:19], v[186:187] op_sel_hi:[1,0]
	v_pk_mul_f32 v[16:17], v[16:17], v[186:187] op_sel_hi:[1,0]
	v_pk_mul_f32 v[14:15], v[14:15], v[186:187] op_sel_hi:[1,0]
	v_pk_mul_f32 v[12:13], v[12:13], v[186:187] op_sel_hi:[1,0]
	v_pk_mul_f32 v[10:11], v[10:11], v[186:187] op_sel_hi:[1,0]
	v_pk_mul_f32 v[8:9], v[8:9], v[186:187] op_sel_hi:[1,0]
	v_pk_mul_f32 v[6:7], v[6:7], v[186:187] op_sel_hi:[1,0]
	v_pk_mul_f32 v[4:5], v[4:5], v[186:187] op_sel_hi:[1,0]
	v_pk_mul_f32 v[2:3], v[2:3], v[186:187] op_sel_hi:[1,0]
	v_mul_f32_e32 v224, v224, v186
	v_add_f32_e32 v186, v187, v188
	v_sub_f32_e32 v82, v82, v186
	v_sub_f32_e32 v83, v83, v186
	v_sub_f32_e32 v84, v84, v186
	v_sub_f32_e32 v85, v85, v186
	v_sub_f32_e32 v86, v86, v186
	v_sub_f32_e32 v87, v87, v186
	v_sub_f32_e32 v88, v88, v186
	v_sub_f32_e32 v89, v89, v186
	v_sub_f32_e32 v90, v90, v186
	v_sub_f32_e32 v91, v91, v186
	v_sub_f32_e32 v92, v92, v186
	v_sub_f32_e32 v93, v93, v186
	v_sub_f32_e32 v94, v94, v186
	v_sub_f32_e32 v95, v95, v186
	v_sub_f32_e32 v96, v96, v186
	v_sub_f32_e32 v97, v97, v186
	v_sub_f32_e32 v66, v66, v186
	v_sub_f32_e32 v67, v67, v186
	v_sub_f32_e32 v68, v68, v186
	v_sub_f32_e32 v69, v69, v186
	v_sub_f32_e32 v70, v70, v186
	v_sub_f32_e32 v71, v71, v186
	v_sub_f32_e32 v72, v72, v186
	v_sub_f32_e32 v73, v73, v186
	v_sub_f32_e32 v74, v74, v186
	v_sub_f32_e32 v75, v75, v186
	v_sub_f32_e32 v76, v76, v186
	v_sub_f32_e32 v77, v77, v186
	v_sub_f32_e32 v78, v78, v186
	v_sub_f32_e32 v79, v79, v186
	v_sub_f32_e32 v80, v80, v186
	v_sub_f32_e32 v81, v81, v186
	v_sub_f32_e32 v188, 0, v187
	v_sub_f32_e32 v189, 0, v187
	v_sub_f32_e32 v190, 0, v187
	v_sub_f32_e32 v191, 0, v187
	v_sub_f32_e32 v192, 0, v187
	v_sub_f32_e32 v193, 0, v187
	v_sub_f32_e32 v194, 0, v187
	v_sub_f32_e32 v195, 0, v187
	v_sub_f32_e32 v196, 0, v187
	v_sub_f32_e32 v197, 0, v187
	v_sub_f32_e32 v198, 0, v187
	v_sub_f32_e32 v199, 0, v187
	v_sub_f32_e32 v200, 0, v187
	v_sub_f32_e32 v201, 0, v187
	v_sub_f32_e32 v202, 0, v187
	v_sub_f32_e32 v203, 0, v187

.Latt3_wdone_9:
.Latt3_wskip_6:
	s_mov_b32 s13, s70
	s_mov_b32 s70, s71
	s_mov_b32 s71, s72
	s_mov_b32 s72, s13
	s_add_i32 s11, s11, 1
	v_add_u32_e32 v209, s70, v215
	v_add_u32_e32 v205, s70, v216
	ds_read_b128 v[226:229], v209
	ds_read_b128 v[236:239], v209 offset:12800
	ds_read_b128 v[240:243], v209 offset:32
	ds_read_b128 v[244:247], v209 offset:12832
	ds_read_b128 v[248:251], v209 offset:64
	ds_read_b128 v[210:213], v209 offset:12864
	s_waitcnt lgkmcnt(5)
	v_mfma_f32_32x32x16_bf16 v[82:97], v[226:229], v[126:129], v[188:203]
	ds_read_b128 v[226:229], v209 offset:96
	s_waitcnt lgkmcnt(5)
	v_mfma_f32_32x32x16_bf16 v[66:81], v[236:239], v[126:129], v[188:203]
	ds_read_b128 v[236:239], v209 offset:12896
	s_waitcnt lgkmcnt(5)
	v_mfma_f32_32x32x16_bf16 v[82:97], v[240:243], v[142:145], v[82:97]
	ds_read_b128 v[240:243], v209 offset:128
	s_waitcnt lgkmcnt(5)
	v_mfma_f32_32x32x16_bf16 v[66:81], v[244:247], v[142:145], v[66:81]
	ds_read_b128 v[244:247], v209 offset:12928
	s_waitcnt lgkmcnt(5)
	v_mfma_f32_32x32x16_bf16 v[82:97], v[248:251], v[146:149], v[82:97]
	ds_read_b128 v[248:251], v209 offset:160
	s_waitcnt lgkmcnt(5)
	v_mfma_f32_32x32x16_bf16 v[66:81], v[210:213], v[146:149], v[66:81]
	ds_read_b128 v[210:213], v209 offset:12960
	s_waitcnt lgkmcnt(5)
	v_mfma_f32_32x32x16_bf16 v[82:97], v[226:229], v[150:153], v[82:97]
	ds_read_b128 v[226:229], v209 offset:192
	s_waitcnt lgkmcnt(5)
	v_mfma_f32_32x32x16_bf16 v[66:81], v[236:239], v[150:153], v[66:81]
	ds_read_b128 v[236:239], v209 offset:12992
	s_waitcnt lgkmcnt(5)
	v_mfma_f32_32x32x16_bf16 v[82:97], v[240:243], v[154:157], v[82:97]
	ds_read_b128 v[240:243], v209 offset:224
	s_waitcnt lgkmcnt(5)
	v_mfma_f32_32x32x16_bf16 v[66:81], v[244:247], v[154:157], v[66:81]
	ds_read_b128 v[244:247], v209 offset:13024
	s_waitcnt lgkmcnt(5)
	v_mfma_f32_32x32x16_bf16 v[82:97], v[248:251], v[158:161], v[82:97]
	ds_read_b128 v[248:251], v209 offset:256
	s_waitcnt lgkmcnt(5)
	v_mfma_f32_32x32x16_bf16 v[66:81], v[210:213], v[158:161], v[66:81]
	ds_read_b128 v[210:213], v209 offset:13056
	s_waitcnt lgkmcnt(5)
	v_mfma_f32_32x32x16_bf16 v[82:97], v[226:229], v[162:165], v[82:97]
	ds_read_b128 v[226:229], v209 offset:288
	s_waitcnt lgkmcnt(5)
	v_mfma_f32_32x32x16_bf16 v[66:81], v[236:239], v[162:165], v[66:81]
	ds_read_b128 v[236:239], v209 offset:13088
	s_waitcnt lgkmcnt(5)
	v_mfma_f32_32x32x16_bf16 v[82:97], v[240:243], v[166:169], v[82:97]
	ds_read_b128 v[240:243], v209 offset:320
	s_waitcnt lgkmcnt(5)
	v_mfma_f32_32x32x16_bf16 v[66:81], v[244:247], v[166:169], v[66:81]
	ds_read_b128 v[244:247], v209 offset:13120
	s_waitcnt lgkmcnt(5)
	v_mfma_f32_32x32x16_bf16 v[82:97], v[248:251], v[170:173], v[82:97]
	ds_read_b128 v[248:251], v209 offset:352
	s_waitcnt lgkmcnt(5)
	v_mfma_f32_32x32x16_bf16 v[66:81], v[210:213], v[170:173], v[66:81]
	ds_read_b128 v[210:213], v209 offset:13152
	s_waitcnt lgkmcnt(5)
	v_mfma_f32_32x32x16_bf16 v[82:97], v[226:229], v[174:177], v[82:97]
	s_waitcnt lgkmcnt(4)
	v_mfma_f32_32x32x16_bf16 v[66:81], v[236:239], v[174:177], v[66:81]
	s_waitcnt lgkmcnt(3)
	v_mfma_f32_32x32x16_bf16 v[82:97], v[240:243], v[178:181], v[82:97]
	s_waitcnt lgkmcnt(2)
	v_mfma_f32_32x32x16_bf16 v[66:81], v[244:247], v[178:181], v[66:81]
	s_waitcnt lgkmcnt(1)
	v_mfma_f32_32x32x16_bf16 v[82:97], v[248:251], v[182:185], v[82:97]
	s_waitcnt lgkmcnt(0)
	v_mfma_f32_32x32x16_bf16 v[66:81], v[210:213], v[182:185], v[66:81]
	s_setprio 2
	ds_read_b128 v[236:239], v205 offset:25600
	ds_read_b128 v[240:243], v205 offset:30208
	ds_read_b128 v[244:247], v205 offset:34816
	ds_read_b128 v[248:251], v205 offset:39424
	ds_read_b128 v[210:213], v205 offset:25632
	s_nop 4
	v_max3_f32 v226, v82, v83, v84
	v_max3_f32 v227, v85, v86, v87
	v_max3_f32 v228, v88, v89, v90
	v_max3_f32 v229, v91, v92, v93
	v_max3_f32 v226, v226, v94, v95
	v_max3_f32 v227, v227, v96, v97
	v_max3_f32 v228, v228, v66, v67
	v_max3_f32 v229, v229, v68, v69
	v_max3_f32 v226, v226, v70, v71
	v_max3_f32 v227, v227, v72, v73
	v_max3_f32 v228, v228, v74, v75
	v_max3_f32 v229, v229, v76, v77
	v_max3_f32 v226, v226, v78, v79
	v_max3_f32 v227, v227, v80, v81
	v_max3_f32 v186, v226, v227, v228
	v_max_f32_e32 v186, v186, v229
	v_mov_b32_e32 v187, v186
	s_nop 1
	v_permlane32_swap_b32_e32 v186, v187
	v_max_f32_e32 v187, v186, v187
	v_sub_f32_e32 v187, v187, v188
	v_add_f32_e32 v186, 0x41380000, v223
	v_cmp_gt_f32_e32 vcc, v187, v186
	s_cbranch_vccz .Latt3_nr_10
	v_max_f32_e32 v186, v187, v187
	v_max_f32_e32 v187, v223, v223
	v_max_f32_e32 v187, v187, v186
	v_sub_f32_e32 v186, v223, v187
	v_exp_f32_e32 v186, v186
	v_mov_b32_e32 v223, v187
	v_pk_mul_f32 v[64:65], v[64:65], v[186:187] op_sel_hi:[1,0]
	v_pk_mul_f32 v[62:63], v[62:63], v[186:187] op_sel_hi:[1,0]
	v_pk_mul_f32 v[60:61], v[60:61], v[186:187] op_sel_hi:[1,0]
	v_pk_mul_f32 v[58:59], v[58:59], v[186:187] op_sel_hi:[1,0]
	v_pk_mul_f32 v[56:57], v[56:57], v[186:187] op_sel_hi:[1,0]
	v_pk_mul_f32 v[54:55], v[54:55], v[186:187] op_sel_hi:[1,0]
	v_pk_mul_f32 v[52:53], v[52:53], v[186:187] op_sel_hi:[1,0]
	v_pk_mul_f32 v[50:51], v[50:51], v[186:187] op_sel_hi:[1,0]
	v_pk_mul_f32 v[48:49], v[48:49], v[186:187] op_sel_hi:[1,0]
	v_pk_mul_f32 v[46:47], v[46:47], v[186:187] op_sel_hi:[1,0]
	v_pk_mul_f32 v[44:45], v[44:45], v[186:187] op_sel_hi:[1,0]
	v_pk_mul_f32 v[42:43], v[42:43], v[186:187] op_sel_hi:[1,0]
	v_pk_mul_f32 v[40:41], v[40:41], v[186:187] op_sel_hi:[1,0]
	v_pk_mul_f32 v[38:39], v[38:39], v[186:187] op_sel_hi:[1,0]
	v_pk_mul_f32 v[36:37], v[36:37], v[186:187] op_sel_hi:[1,0]
	v_pk_mul_f32 v[34:35], v[34:35], v[186:187] op_sel_hi:[1,0]
	v_pk_mul_f32 v[32:33], v[32:33], v[186:187] op_sel_hi:[1,0]
	v_pk_mul_f32 v[30:31], v[30:31], v[186:187] op_sel_hi:[1,0]
	v_pk_mul_f32 v[28:29], v[28:29], v[186:187] op_sel_hi:[1,0]
	v_pk_mul_f32 v[26:27], v[26:27], v[186:187] op_sel_hi:[1,0]
	v_pk_mul_f32 v[24:25], v[24:25], v[186:187] op_sel_hi:[1,0]
	v_pk_mul_f32 v[22:23], v[22:23], v[186:187] op_sel_hi:[1,0]
	v_pk_mul_f32 v[20:21], v[20:21], v[186:187] op_sel_hi:[1,0]
	v_pk_mul_f32 v[18:19], v[18:19], v[186:187] op_sel_hi:[1,0]
	v_pk_mul_f32 v[16:17], v[16:17], v[186:187] op_sel_hi:[1,0]
	v_pk_mul_f32 v[14:15], v[14:15], v[186:187] op_sel_hi:[1,0]
	v_pk_mul_f32 v[12:13], v[12:13], v[186:187] op_sel_hi:[1,0]
	v_pk_mul_f32 v[10:11], v[10:11], v[186:187] op_sel_hi:[1,0]
	v_pk_mul_f32 v[8:9], v[8:9], v[186:187] op_sel_hi:[1,0]
	v_pk_mul_f32 v[6:7], v[6:7], v[186:187] op_sel_hi:[1,0]
	v_pk_mul_f32 v[4:5], v[4:5], v[186:187] op_sel_hi:[1,0]
	v_pk_mul_f32 v[2:3], v[2:3], v[186:187] op_sel_hi:[1,0]
	v_mul_f32_e32 v225, v225, v186
	v_add_f32_e32 v186, v187, v188
	v_sub_f32_e32 v82, v82, v186
	v_sub_f32_e32 v83, v83, v186
	v_sub_f32_e32 v84, v84, v186
	v_sub_f32_e32 v85, v85, v186
	v_sub_f32_e32 v86, v86, v186
	v_sub_f32_e32 v87, v87, v186
	v_sub_f32_e32 v88, v88, v186
	v_sub_f32_e32 v89, v89, v186
	v_sub_f32_e32 v90, v90, v186
	v_sub_f32_e32 v91, v91, v186
	v_sub_f32_e32 v92, v92, v186
	v_sub_f32_e32 v93, v93, v186
	v_sub_f32_e32 v94, v94, v186
	v_sub_f32_e32 v95, v95, v186
	v_sub_f32_e32 v96, v96, v186
	v_sub_f32_e32 v97, v97, v186
	v_sub_f32_e32 v66, v66, v186
	v_sub_f32_e32 v67, v67, v186
	v_sub_f32_e32 v68, v68, v186
	v_sub_f32_e32 v69, v69, v186
	v_sub_f32_e32 v70, v70, v186
	v_sub_f32_e32 v71, v71, v186
	v_sub_f32_e32 v72, v72, v186
	v_sub_f32_e32 v73, v73, v186
	v_sub_f32_e32 v74, v74, v186
	v_sub_f32_e32 v75, v75, v186
	v_sub_f32_e32 v76, v76, v186
	v_sub_f32_e32 v77, v77, v186
	v_sub_f32_e32 v78, v78, v186
	v_sub_f32_e32 v79, v79, v186
	v_sub_f32_e32 v80, v80, v186
	v_sub_f32_e32 v81, v81, v186
	v_sub_f32_e32 v188, 0, v187
	v_sub_f32_e32 v189, 0, v187
	v_sub_f32_e32 v190, 0, v187
	v_sub_f32_e32 v191, 0, v187
	v_sub_f32_e32 v192, 0, v187
	v_sub_f32_e32 v193, 0, v187
	v_sub_f32_e32 v194, 0, v187
	v_sub_f32_e32 v195, 0, v187
	v_sub_f32_e32 v196, 0, v187
	v_sub_f32_e32 v197, 0, v187
	v_sub_f32_e32 v198, 0, v187
	v_sub_f32_e32 v199, 0, v187
	v_sub_f32_e32 v200, 0, v187
	v_sub_f32_e32 v201, 0, v187
	v_sub_f32_e32 v202, 0, v187
	v_sub_f32_e32 v203, 0, v187

.Latt3_B_loop:
	v_add_u32_e32 v209, s70, v215
	v_add_u32_e32 v205, s70, v216
	ds_read_b128 v[226:229], v209
	ds_read_b128 v[236:239], v209 offset:12800
	ds_read_b128 v[240:243], v209 offset:32
	ds_read_b128 v[244:247], v209 offset:12832
	ds_read_b128 v[248:251], v209 offset:64
	ds_read_b128 v[210:213], v209 offset:12864
	s_waitcnt lgkmcnt(5)
	v_mfma_f32_32x32x16_bf16 v[82:97], v[226:229], v[126:129], v[188:203]
	ds_read_b128 v[226:229], v209 offset:96
	s_waitcnt lgkmcnt(5)
	v_mfma_f32_32x32x16_bf16 v[66:81], v[236:239], v[126:129], v[188:203]
	ds_read_b128 v[236:239], v209 offset:12896
	s_waitcnt lgkmcnt(5)
	v_mfma_f32_32x32x16_bf16 v[82:97], v[240:243], v[142:145], v[82:97]
	ds_read_b128 v[240:243], v209 offset:128
	s_waitcnt lgkmcnt(5)
	v_mfma_f32_32x32x16_bf16 v[66:81], v[244:247], v[142:145], v[66:81]
	ds_read_b128 v[244:247], v209 offset:12928
	s_waitcnt lgkmcnt(5)
	v_mfma_f32_32x32x16_bf16 v[82:97], v[248:251], v[146:149], v[82:97]
	ds_read_b128 v[248:251], v209 offset:160
	s_waitcnt lgkmcnt(5)
	v_mfma_f32_32x32x16_bf16 v[66:81], v[210:213], v[146:149], v[66:81]
	ds_read_b128 v[210:213], v209 offset:12960
	s_waitcnt lgkmcnt(5)
	v_mfma_f32_32x32x16_bf16 v[82:97], v[226:229], v[150:153], v[82:97]
	ds_read_b128 v[226:229], v209 offset:192
	s_waitcnt lgkmcnt(5)
	v_mfma_f32_32x32x16_bf16 v[66:81], v[236:239], v[150:153], v[66:81]
	ds_read_b128 v[236:239], v209 offset:12992
	s_waitcnt lgkmcnt(5)
	v_mfma_f32_32x32x16_bf16 v[82:97], v[240:243], v[154:157], v[82:97]
	ds_read_b128 v[240:243], v209 offset:224
	s_waitcnt lgkmcnt(5)
	v_mfma_f32_32x32x16_bf16 v[66:81], v[244:247], v[154:157], v[66:81]
	ds_read_b128 v[244:247], v209 offset:13024
	s_waitcnt lgkmcnt(5)
	v_mfma_f32_32x32x16_bf16 v[82:97], v[248:251], v[158:161], v[82:97]
	ds_read_b128 v[248:251], v209 offset:256
	s_waitcnt lgkmcnt(5)
	v_mfma_f32_32x32x16_bf16 v[66:81], v[210:213], v[158:161], v[66:81]
	ds_read_b128 v[210:213], v209 offset:13056
	s_waitcnt lgkmcnt(5)
	v_mfma_f32_32x32x16_bf16 v[82:97], v[226:229], v[162:165], v[82:97]
	ds_read_b128 v[226:229], v209 offset:288
	s_waitcnt lgkmcnt(5)
	v_mfma_f32_32x32x16_bf16 v[66:81], v[236:239], v[162:165], v[66:81]
	ds_read_b128 v[236:239], v209 offset:13088
	s_waitcnt lgkmcnt(5)
	v_mfma_f32_32x32x16_bf16 v[82:97], v[240:243], v[166:169], v[82:97]
	ds_read_b128 v[240:243], v209 offset:320
	s_waitcnt lgkmcnt(5)
	v_mfma_f32_32x32x16_bf16 v[66:81], v[244:247], v[166:169], v[66:81]
	ds_read_b128 v[244:247], v209 offset:13120
	s_waitcnt lgkmcnt(5)
	v_mfma_f32_32x32x16_bf16 v[82:97], v[248:251], v[170:173], v[82:97]
	ds_read_b128 v[248:251], v209 offset:352
	s_waitcnt lgkmcnt(5)
	v_mfma_f32_32x32x16_bf16 v[66:81], v[210:213], v[170:173], v[66:81]
	ds_read_b128 v[210:213], v209 offset:13152
	s_waitcnt lgkmcnt(5)
	v_mfma_f32_32x32x16_bf16 v[82:97], v[226:229], v[174:177], v[82:97]
	s_waitcnt lgkmcnt(4)
	v_mfma_f32_32x32x16_bf16 v[66:81], v[236:239], v[174:177], v[66:81]
	s_waitcnt lgkmcnt(3)
	v_mfma_f32_32x32x16_bf16 v[82:97], v[240:243], v[178:181], v[82:97]
	s_waitcnt lgkmcnt(2)
	v_mfma_f32_32x32x16_bf16 v[66:81], v[244:247], v[178:181], v[66:81]
	s_waitcnt lgkmcnt(1)
	v_mfma_f32_32x32x16_bf16 v[82:97], v[248:251], v[182:185], v[82:97]
	s_waitcnt lgkmcnt(0)
	s_barrier
	v_mfma_f32_32x32x16_bf16 v[66:81], v[210:213], v[182:185], v[66:81]
	s_setprio 2
	ds_read_b128 v[236:239], v205 offset:25600
	ds_read_b128 v[240:243], v205 offset:30208
	ds_read_b128 v[244:247], v205 offset:34816
	ds_read_b128 v[248:251], v205 offset:39424
	ds_read_b128 v[210:213], v205 offset:25632
	s_nop 4
	v_max3_f32 v226, v82, v83, v84
	v_max3_f32 v227, v85, v86, v87
	v_max3_f32 v228, v88, v89, v90
	v_max3_f32 v229, v91, v92, v93
	v_max3_f32 v226, v226, v94, v95
	v_max3_f32 v227, v227, v96, v97
	v_max3_f32 v228, v228, v66, v67
	v_max3_f32 v229, v229, v68, v69
	v_max3_f32 v226, v226, v70, v71
	v_max3_f32 v227, v227, v72, v73
	v_max3_f32 v228, v228, v74, v75
	v_max3_f32 v229, v229, v76, v77
	v_max3_f32 v226, v226, v78, v79
	v_max3_f32 v227, v227, v80, v81
	v_max3_f32 v186, v226, v227, v228
	v_max_f32_e32 v186, v186, v229
	v_mov_b32_e32 v187, v186
	s_nop 1
	v_permlane32_swap_b32_e32 v186, v187
	v_max_f32_e32 v187, v186, v187
	v_sub_f32_e32 v187, v187, v188
	v_add_f32_e32 v186, 0x41380000, v223
	v_cmp_gt_f32_e32 vcc, v187, v186
	s_cbranch_vccz .Latt3_nr_15
	v_max_f32_e32 v186, v187, v187
	v_max_f32_e32 v187, v223, v223
	v_max_f32_e32 v187, v187, v186
	v_sub_f32_e32 v186, v223, v187
	v_exp_f32_e32 v186, v186
	v_mov_b32_e32 v223, v187
	v_pk_mul_f32 v[64:65], v[64:65], v[186:187] op_sel_hi:[1,0]
	v_pk_mul_f32 v[62:63], v[62:63], v[186:187] op_sel_hi:[1,0]
	v_pk_mul_f32 v[60:61], v[60:61], v[186:187] op_sel_hi:[1,0]
	v_pk_mul_f32 v[58:59], v[58:59], v[186:187] op_sel_hi:[1,0]
	v_pk_mul_f32 v[56:57], v[56:57], v[186:187] op_sel_hi:[1,0]
	v_pk_mul_f32 v[54:55], v[54:55], v[186:187] op_sel_hi:[1,0]
	v_pk_mul_f32 v[52:53], v[52:53], v[186:187] op_sel_hi:[1,0]
	v_pk_mul_f32 v[50:51], v[50:51], v[186:187] op_sel_hi:[1,0]
	v_pk_mul_f32 v[48:49], v[48:49], v[186:187] op_sel_hi:[1,0]
	v_pk_mul_f32 v[46:47], v[46:47], v[186:187] op_sel_hi:[1,0]
	v_pk_mul_f32 v[44:45], v[44:45], v[186:187] op_sel_hi:[1,0]
	v_pk_mul_f32 v[42:43], v[42:43], v[186:187] op_sel_hi:[1,0]
	v_pk_mul_f32 v[40:41], v[40:41], v[186:187] op_sel_hi:[1,0]
	v_pk_mul_f32 v[38:39], v[38:39], v[186:187] op_sel_hi:[1,0]
	v_pk_mul_f32 v[36:37], v[36:37], v[186:187] op_sel_hi:[1,0]
	v_pk_mul_f32 v[34:35], v[34:35], v[186:187] op_sel_hi:[1,0]
	v_pk_mul_f32 v[32:33], v[32:33], v[186:187] op_sel_hi:[1,0]
	v_pk_mul_f32 v[30:31], v[30:31], v[186:187] op_sel_hi:[1,0]
	v_pk_mul_f32 v[28:29], v[28:29], v[186:187] op_sel_hi:[1,0]
	v_pk_mul_f32 v[26:27], v[26:27], v[186:187] op_sel_hi:[1,0]
	v_pk_mul_f32 v[24:25], v[24:25], v[186:187] op_sel_hi:[1,0]
	v_pk_mul_f32 v[22:23], v[22:23], v[186:187] op_sel_hi:[1,0]
	v_pk_mul_f32 v[20:21], v[20:21], v[186:187] op_sel_hi:[1,0]
	v_pk_mul_f32 v[18:19], v[18:19], v[186:187] op_sel_hi:[1,0]
	v_pk_mul_f32 v[16:17], v[16:17], v[186:187] op_sel_hi:[1,0]
	v_pk_mul_f32 v[14:15], v[14:15], v[186:187] op_sel_hi:[1,0]
	v_pk_mul_f32 v[12:13], v[12:13], v[186:187] op_sel_hi:[1,0]
	v_pk_mul_f32 v[10:11], v[10:11], v[186:187] op_sel_hi:[1,0]
	v_pk_mul_f32 v[8:9], v[8:9], v[186:187] op_sel_hi:[1,0]
	v_pk_mul_f32 v[6:7], v[6:7], v[186:187] op_sel_hi:[1,0]
	v_pk_mul_f32 v[4:5], v[4:5], v[186:187] op_sel_hi:[1,0]
	v_pk_mul_f32 v[2:3], v[2:3], v[186:187] op_sel_hi:[1,0]
	v_mul_f32_e32 v224, v224, v186
	v_add_f32_e32 v186, v187, v188
	v_sub_f32_e32 v82, v82, v186
	v_sub_f32_e32 v83, v83, v186
	v_sub_f32_e32 v84, v84, v186
	v_sub_f32_e32 v85, v85, v186
	v_sub_f32_e32 v86, v86, v186
	v_sub_f32_e32 v87, v87, v186
	v_sub_f32_e32 v88, v88, v186
	v_sub_f32_e32 v89, v89, v186
	v_sub_f32_e32 v90, v90, v186
	v_sub_f32_e32 v91, v91, v186
	v_sub_f32_e32 v92, v92, v186
	v_sub_f32_e32 v93, v93, v186
	v_sub_f32_e32 v94, v94, v186
	v_sub_f32_e32 v95, v95, v186
	v_sub_f32_e32 v96, v96, v186
	v_sub_f32_e32 v97, v97, v186
	v_sub_f32_e32 v66, v66, v186
	v_sub_f32_e32 v67, v67, v186
	v_sub_f32_e32 v68, v68, v186
	v_sub_f32_e32 v69, v69, v186
	v_sub_f32_e32 v70, v70, v186
	v_sub_f32_e32 v71, v71, v186
	v_sub_f32_e32 v72, v72, v186
	v_sub_f32_e32 v73, v73, v186
	v_sub_f32_e32 v74, v74, v186
	v_sub_f32_e32 v75, v75, v186
	v_sub_f32_e32 v76, v76, v186
	v_sub_f32_e32 v77, v77, v186
	v_sub_f32_e32 v78, v78, v186
	v_sub_f32_e32 v79, v79, v186
	v_sub_f32_e32 v80, v80, v186
	v_sub_f32_e32 v81, v81, v186
	v_sub_f32_e32 v188, 0, v187
	v_sub_f32_e32 v189, 0, v187
	v_sub_f32_e32 v190, 0, v187
	v_sub_f32_e32 v191, 0, v187
	v_sub_f32_e32 v192, 0, v187
	v_sub_f32_e32 v193, 0, v187
	v_sub_f32_e32 v194, 0, v187
	v_sub_f32_e32 v195, 0, v187
	v_sub_f32_e32 v196, 0, v187
	v_sub_f32_e32 v197, 0, v187
	v_sub_f32_e32 v198, 0, v187
	v_sub_f32_e32 v199, 0, v187
	v_sub_f32_e32 v200, 0, v187
	v_sub_f32_e32 v201, 0, v187
	v_sub_f32_e32 v202, 0, v187
	v_sub_f32_e32 v203, 0, v187

.Latt3_wdone_19:
.Latt3_wskip_16:
	s_mov_b32 s13, s70
	s_mov_b32 s70, s71
	s_mov_b32 s71, s72
	s_mov_b32 s72, s13
	s_add_i32 s11, s11, 1
	v_add_u32_e32 v209, s70, v215
	v_add_u32_e32 v205, s70, v216
	ds_read_b128 v[226:229], v209
	ds_read_b128 v[236:239], v209 offset:12800
	ds_read_b128 v[240:243], v209 offset:32
	ds_read_b128 v[244:247], v209 offset:12832
	ds_read_b128 v[248:251], v209 offset:64
	ds_read_b128 v[210:213], v209 offset:12864
	s_waitcnt lgkmcnt(5)
	v_mfma_f32_32x32x16_bf16 v[82:97], v[226:229], v[126:129], v[188:203]
	ds_read_b128 v[226:229], v209 offset:96
	s_waitcnt lgkmcnt(5)
	v_mfma_f32_32x32x16_bf16 v[66:81], v[236:239], v[126:129], v[188:203]
	ds_read_b128 v[236:239], v209 offset:12896
	s_waitcnt lgkmcnt(5)
	v_mfma_f32_32x32x16_bf16 v[82:97], v[240:243], v[142:145], v[82:97]
	ds_read_b128 v[240:243], v209 offset:128
	s_waitcnt lgkmcnt(5)
	v_mfma_f32_32x32x16_bf16 v[66:81], v[244:247], v[142:145], v[66:81]
	ds_read_b128 v[244:247], v209 offset:12928
	s_waitcnt lgkmcnt(5)
	v_mfma_f32_32x32x16_bf16 v[82:97], v[248:251], v[146:149], v[82:97]
	ds_read_b128 v[248:251], v209 offset:160
	s_waitcnt lgkmcnt(5)
	v_mfma_f32_32x32x16_bf16 v[66:81], v[210:213], v[146:149], v[66:81]
	ds_read_b128 v[210:213], v209 offset:12960
	s_waitcnt lgkmcnt(5)
	v_mfma_f32_32x32x16_bf16 v[82:97], v[226:229], v[150:153], v[82:97]
	ds_read_b128 v[226:229], v209 offset:192
	s_waitcnt lgkmcnt(5)
	v_mfma_f32_32x32x16_bf16 v[66:81], v[236:239], v[150:153], v[66:81]
	ds_read_b128 v[236:239], v209 offset:12992
	s_waitcnt lgkmcnt(5)
	v_mfma_f32_32x32x16_bf16 v[82:97], v[240:243], v[154:157], v[82:97]
	ds_read_b128 v[240:243], v209 offset:224
	s_waitcnt lgkmcnt(5)
	v_mfma_f32_32x32x16_bf16 v[66:81], v[244:247], v[154:157], v[66:81]
	ds_read_b128 v[244:247], v209 offset:13024
	s_waitcnt lgkmcnt(5)
	v_mfma_f32_32x32x16_bf16 v[82:97], v[248:251], v[158:161], v[82:97]
	ds_read_b128 v[248:251], v209 offset:256
	s_waitcnt lgkmcnt(5)
	v_mfma_f32_32x32x16_bf16 v[66:81], v[210:213], v[158:161], v[66:81]
	ds_read_b128 v[210:213], v209 offset:13056
	s_waitcnt lgkmcnt(5)
	v_mfma_f32_32x32x16_bf16 v[82:97], v[226:229], v[162:165], v[82:97]
	ds_read_b128 v[226:229], v209 offset:288
	s_waitcnt lgkmcnt(5)
	v_mfma_f32_32x32x16_bf16 v[66:81], v[236:239], v[162:165], v[66:81]
	ds_read_b128 v[236:239], v209 offset:13088
	s_waitcnt lgkmcnt(5)
	v_mfma_f32_32x32x16_bf16 v[82:97], v[240:243], v[166:169], v[82:97]
	ds_read_b128 v[240:243], v209 offset:320
	s_waitcnt lgkmcnt(5)
	v_mfma_f32_32x32x16_bf16 v[66:81], v[244:247], v[166:169], v[66:81]
	ds_read_b128 v[244:247], v209 offset:13120
	s_waitcnt lgkmcnt(5)
	v_mfma_f32_32x32x16_bf16 v[82:97], v[248:251], v[170:173], v[82:97]
	ds_read_b128 v[248:251], v209 offset:352
	s_waitcnt lgkmcnt(5)
	v_mfma_f32_32x32x16_bf16 v[66:81], v[210:213], v[170:173], v[66:81]
	ds_read_b128 v[210:213], v209 offset:13152
	s_waitcnt lgkmcnt(5)
	v_mfma_f32_32x32x16_bf16 v[82:97], v[226:229], v[174:177], v[82:97]
	s_waitcnt lgkmcnt(4)
	v_mfma_f32_32x32x16_bf16 v[66:81], v[236:239], v[174:177], v[66:81]
	s_waitcnt lgkmcnt(3)
	v_mfma_f32_32x32x16_bf16 v[82:97], v[240:243], v[178:181], v[82:97]
	s_waitcnt lgkmcnt(2)
	v_mfma_f32_32x32x16_bf16 v[66:81], v[244:247], v[178:181], v[66:81]
	s_waitcnt lgkmcnt(1)
	v_mfma_f32_32x32x16_bf16 v[82:97], v[248:251], v[182:185], v[82:97]
	s_waitcnt lgkmcnt(0)
	s_barrier
	v_mfma_f32_32x32x16_bf16 v[66:81], v[210:213], v[182:185], v[66:81]
	s_setprio 2
	ds_read_b128 v[236:239], v205 offset:25600
	ds_read_b128 v[240:243], v205 offset:30208
	ds_read_b128 v[244:247], v205 offset:34816
	ds_read_b128 v[248:251], v205 offset:39424
	ds_read_b128 v[210:213], v205 offset:25632
	s_nop 4
	v_max3_f32 v226, v82, v83, v84
	v_max3_f32 v227, v85, v86, v87
	v_max3_f32 v228, v88, v89, v90
	v_max3_f32 v229, v91, v92, v93
	v_max3_f32 v226, v226, v94, v95
	v_max3_f32 v227, v227, v96, v97
	v_max3_f32 v228, v228, v66, v67
	v_max3_f32 v229, v229, v68, v69
	v_max3_f32 v226, v226, v70, v71
	v_max3_f32 v227, v227, v72, v73
	v_max3_f32 v228, v228, v74, v75
	v_max3_f32 v229, v229, v76, v77
	v_max3_f32 v226, v226, v78, v79
	v_max3_f32 v227, v227, v80, v81
	v_max3_f32 v186, v226, v227, v228
	v_max_f32_e32 v186, v186, v229
	v_mov_b32_e32 v187, v186
	s_nop 1
	v_permlane32_swap_b32_e32 v186, v187
	v_max_f32_e32 v187, v186, v187
	v_sub_f32_e32 v187, v187, v188
	v_add_f32_e32 v186, 0x41380000, v223
	v_cmp_gt_f32_e32 vcc, v187, v186
	s_cbranch_vccz .Latt3_nr_20
	v_max_f32_e32 v186, v187, v187
	v_max_f32_e32 v187, v223, v223
	v_max_f32_e32 v187, v187, v186
	v_sub_f32_e32 v186, v223, v187
	v_exp_f32_e32 v186, v186
	v_mov_b32_e32 v223, v187
	v_pk_mul_f32 v[64:65], v[64:65], v[186:187] op_sel_hi:[1,0]
	v_pk_mul_f32 v[62:63], v[62:63], v[186:187] op_sel_hi:[1,0]
	v_pk_mul_f32 v[60:61], v[60:61], v[186:187] op_sel_hi:[1,0]
	v_pk_mul_f32 v[58:59], v[58:59], v[186:187] op_sel_hi:[1,0]
	v_pk_mul_f32 v[56:57], v[56:57], v[186:187] op_sel_hi:[1,0]
	v_pk_mul_f32 v[54:55], v[54:55], v[186:187] op_sel_hi:[1,0]
	v_pk_mul_f32 v[52:53], v[52:53], v[186:187] op_sel_hi:[1,0]
	v_pk_mul_f32 v[50:51], v[50:51], v[186:187] op_sel_hi:[1,0]
	v_pk_mul_f32 v[48:49], v[48:49], v[186:187] op_sel_hi:[1,0]
	v_pk_mul_f32 v[46:47], v[46:47], v[186:187] op_sel_hi:[1,0]
	v_pk_mul_f32 v[44:45], v[44:45], v[186:187] op_sel_hi:[1,0]
	v_pk_mul_f32 v[42:43], v[42:43], v[186:187] op_sel_hi:[1,0]
	v_pk_mul_f32 v[40:41], v[40:41], v[186:187] op_sel_hi:[1,0]
	v_pk_mul_f32 v[38:39], v[38:39], v[186:187] op_sel_hi:[1,0]
	v_pk_mul_f32 v[36:37], v[36:37], v[186:187] op_sel_hi:[1,0]
	v_pk_mul_f32 v[34:35], v[34:35], v[186:187] op_sel_hi:[1,0]
	v_pk_mul_f32 v[32:33], v[32:33], v[186:187] op_sel_hi:[1,0]
	v_pk_mul_f32 v[30:31], v[30:31], v[186:187] op_sel_hi:[1,0]
	v_pk_mul_f32 v[28:29], v[28:29], v[186:187] op_sel_hi:[1,0]
	v_pk_mul_f32 v[26:27], v[26:27], v[186:187] op_sel_hi:[1,0]
	v_pk_mul_f32 v[24:25], v[24:25], v[186:187] op_sel_hi:[1,0]
	v_pk_mul_f32 v[22:23], v[22:23], v[186:187] op_sel_hi:[1,0]
	v_pk_mul_f32 v[20:21], v[20:21], v[186:187] op_sel_hi:[1,0]
	v_pk_mul_f32 v[18:19], v[18:19], v[186:187] op_sel_hi:[1,0]
	v_pk_mul_f32 v[16:17], v[16:17], v[186:187] op_sel_hi:[1,0]
	v_pk_mul_f32 v[14:15], v[14:15], v[186:187] op_sel_hi:[1,0]
	v_pk_mul_f32 v[12:13], v[12:13], v[186:187] op_sel_hi:[1,0]
	v_pk_mul_f32 v[10:11], v[10:11], v[186:187] op_sel_hi:[1,0]
	v_pk_mul_f32 v[8:9], v[8:9], v[186:187] op_sel_hi:[1,0]
	v_pk_mul_f32 v[6:7], v[6:7], v[186:187] op_sel_hi:[1,0]
	v_pk_mul_f32 v[4:5], v[4:5], v[186:187] op_sel_hi:[1,0]
	v_pk_mul_f32 v[2:3], v[2:3], v[186:187] op_sel_hi:[1,0]
	v_mul_f32_e32 v225, v225, v186
	v_add_f32_e32 v186, v187, v188
	v_sub_f32_e32 v82, v82, v186
	v_sub_f32_e32 v83, v83, v186
	v_sub_f32_e32 v84, v84, v186
	v_sub_f32_e32 v85, v85, v186
	v_sub_f32_e32 v86, v86, v186
	v_sub_f32_e32 v87, v87, v186
	v_sub_f32_e32 v88, v88, v186
	v_sub_f32_e32 v89, v89, v186
	v_sub_f32_e32 v90, v90, v186
	v_sub_f32_e32 v91, v91, v186
	v_sub_f32_e32 v92, v92, v186
	v_sub_f32_e32 v93, v93, v186
	v_sub_f32_e32 v94, v94, v186
	v_sub_f32_e32 v95, v95, v186
	v_sub_f32_e32 v96, v96, v186
	v_sub_f32_e32 v97, v97, v186
	v_sub_f32_e32 v66, v66, v186
	v_sub_f32_e32 v67, v67, v186
	v_sub_f32_e32 v68, v68, v186
	v_sub_f32_e32 v69, v69, v186
	v_sub_f32_e32 v70, v70, v186
	v_sub_f32_e32 v71, v71, v186
	v_sub_f32_e32 v72, v72, v186
	v_sub_f32_e32 v73, v73, v186
	v_sub_f32_e32 v74, v74, v186
	v_sub_f32_e32 v75, v75, v186
	v_sub_f32_e32 v76, v76, v186
	v_sub_f32_e32 v77, v77, v186
	v_sub_f32_e32 v78, v78, v186
	v_sub_f32_e32 v79, v79, v186
	v_sub_f32_e32 v80, v80, v186
	v_sub_f32_e32 v81, v81, v186
	v_sub_f32_e32 v188, 0, v187
	v_sub_f32_e32 v189, 0, v187
	v_sub_f32_e32 v190, 0, v187
	v_sub_f32_e32 v191, 0, v187
	v_sub_f32_e32 v192, 0, v187
	v_sub_f32_e32 v193, 0, v187
	v_sub_f32_e32 v194, 0, v187
	v_sub_f32_e32 v195, 0, v187
	v_sub_f32_e32 v196, 0, v187
	v_sub_f32_e32 v197, 0, v187
	v_sub_f32_e32 v198, 0, v187
	v_sub_f32_e32 v199, 0, v187
	v_sub_f32_e32 v200, 0, v187
	v_sub_f32_e32 v201, 0, v187
	v_sub_f32_e32 v202, 0, v187
	v_sub_f32_e32 v203, 0, v187
